# v21 + QKV-L0 rope epilogue: rope-table loads of groups 3-8 issued early into a private double buffer (v232-247), counted vmcnt lets the store in between fly
# baseline (speedup 1.0000x reference)
; __device__ __forceinline__ unsigned cvt_pk_bf16(float lo, float hi) { unsigned r; asm volatile("v_cvt_pk_bf16_f32 %0, %1, %2" : "=v"(r) : "v"(lo), "v"(hi)); return r; }
; #define ropetab WSP(float, WS_ROPE)
;     __device__ __forceinline__ void operator()(f32x4 (&acc)[2][2][4][2], const Unit& u, int wr, int wc, int fr, int fq, PG8_LAS unsigned char* sp) const {
;     ...
;             const float* gp = (isq ? qgain : kgain) + 32 * (wc & 1) + 8 * fq; const float gs = isq ? qscale : 1.0f;
;             const f32x4 gl0 = *(const f32x4*)(gp) * gs, gl1 = *(const f32x4*)(gp + 4) * gs;
; #pragma unroll
;             for (int ai = 0; ai < 2; ++ai)
; #pragma unroll
;                 for (int m = 0; m < 4; ++m) { const int row = row0 + ai * HALF + m * 16;
;                     f32x4 cs0 = {1.f, 0.f, 1.f, 0.f}, cs1 = {1.f, 0.f, 1.f, 0.f};
;                     if (ROPE) { const int t = (row < 65536) ? (row & 2047) : (row - 65536); const int pos = (wc & 1) ? (t & 63) : (t >> 6);
;                         const float* tp = ropetab + (size_t)(pos * 16 + 4 * fq) * 2; cs0 = *(const f32x4*)(tp); cs1 = *(const f32x4*)(tp + 4); }
;                     bf16_t* rowp = base + (size_t)row * ldc + col0;
; #pragma unroll
;                     for (int bj = 0; bj < 2; ++bj) { const int idx = (ai * 4 + m) * 2 + bj;
;                         const float tot = part[idx] + xch[(wid ^ 1) * 256 + idx * 16 + fr]; const float rinv = __builtin_amdgcn_rsqf(tot * (1.0f / 64.0f) + EPI_EPS);
;                         f32x4 v0 = acc[ai][bj][m][0] * rinv * gl0, v1 = acc[ai][bj][m][1] * rinv * gl1;
;                         if (ROPE) { const f32x4 a = v0, b = v1;
;                             v0[0] = a[0] * cs0[0] - a[1] * cs0[1]; v0[1] = a[0] * cs0[1] + a[1] * cs0[0]; v0[2] = a[2] * cs0[2] - a[3] * cs0[3]; v0[3] = a[2] * cs0[3] + a[3] * cs0[2];
;                             v1[0] = b[0] * cs1[0] - b[1] * cs1[1]; v1[1] = b[0] * cs1[1] + b[1] * cs1[0]; v1[2] = b[2] * cs1[2] - b[3] * cs1[3]; v1[3] = b[2] * cs1[3] + b[3] * cs1[2]; }
;                         u32x4 w; w.x = cvt_pk_bf16(v0[0], v0[1]); w.y = cvt_pk_bf16(v0[2], v0[3]); w.z = cvt_pk_bf16(v1[0], v1[1]); w.w = cvt_pk_bf16(v1[2], v1[3]);
;                         *(u32x4*)(rowp + bj * HALF) = w; } }
.LBB0_551:
	v_and_b32_e32 v160, 0x7cf, v148
	v_add_u32_e32 v161, 0xffff0000, v148
	v_cmp_gt_i32_e32 vcc, s77, v148
	s_and_b64 s[34:35], s[10:11], exec
	s_cselect_b32 s34, s20, s22
	v_cndmask_b32_e32 v160, v161, v160, vcc
	v_and_b32_e32 v161, 15, v160
	v_ashrrev_i32_e32 v160, 6, v160
	s_cselect_b32 s14, s39, s69
	s_cselect_b32 s15, s38, s68
	s_cselect_b32 s35, s21, s23
	s_add_u32 s34, s34, s87
	v_cndmask_b32_e64 v160, v161, v160, s[6:7]
	s_addc_u32 s35, s35, 0
	v_lshl_or_b32 v160, v160, 4, v164
	global_load_dwordx4 v[128:131], v187, s[34:35] offset:16
	global_load_dwordx4 v[206:209], v187, s[34:35]
	v_ashrrev_i32_e32 v161, 31, v160
	v_lshl_add_u64 v[160:161], v[160:161], 3, s[40:41]
	global_load_dwordx4 v[210:213], v[160:161], off
	global_load_dwordx4 v[214:217], v[160:161], off offset:16
	ds_read_b32 v161, v166
	v_bitop3_b32 v218, v148, s88, 16 bitop3:0xc8
	v_add_u32_e32 v219, 0xffff0010, v148
	v_cmp_gt_i32_e32 vcc, s77, v154
	v_cndmask_b32_e64 v160, 1.0, v189, s[10:11]
	s_waitcnt lgkmcnt(0)
	v_add_f32_e32 v161, v205, v161
	v_fmamk_f32 v161, v161, 0x3c800000, v188
	v_rsq_f32_e32 v220, v161
	v_cndmask_b32_e32 v221, v219, v218, vcc
	v_and_b32_e32 v205, 31, v221
	v_ashrrev_i32_e32 v228, 6, v221
	v_pk_mul_f32 v[222:223], v[126:127], v[220:221] op_sel_hi:[1,0]
	v_pk_mul_f32 v[224:225], v[124:125], v[220:221] op_sel_hi:[1,0]
	v_pk_mul_f32 v[226:227], v[122:123], v[220:221] op_sel_hi:[1,0]
	v_pk_mul_f32 v[220:221], v[120:121], v[220:221] op_sel_hi:[1,0]
	s_and_b64 s[10:11], s[10:11], exec
	v_mov_b32_e32 v218, s15
	v_mov_b32_e32 v219, s14
	s_cselect_b32 s10, 10, 8
	v_cmp_gt_i32_e32 vcc, s77, v152
	s_waitcnt vmcnt(0)
	v_pk_mul_f32 v[126:127], v[160:161], v[128:129] op_sel_hi:[0,1]
	v_pk_mul_f32 v[122:123], v[160:161], v[206:207] op_sel_hi:[0,1]
	v_pk_mul_f32 v[120:121], v[160:161], v[208:209] op_sel_hi:[0,1]
	v_pk_mul_f32 v[124:125], v[160:161], v[130:131] op_sel_hi:[0,1]
	v_pk_mul_f32 v[130:131], v[122:123], v[224:225]
	v_pk_mul_f32 v[206:207], v[126:127], v[220:221]
	v_pk_mul_f32 v[128:129], v[120:121], v[222:223]
	v_pk_mul_f32 v[160:161], v[124:125], v[226:227]
	v_pk_mul_f32 v[208:209], v[210:211], v[130:131]
	v_pk_mul_f32 v[130:131], v[210:211], v[130:131] op_sel:[1,0] op_sel_hi:[0,1]
	v_pk_mul_f32 v[222:223], v[214:215], v[206:207]
	v_pk_mul_f32 v[206:207], v[214:215], v[206:207] op_sel:[1,0] op_sel_hi:[0,1]
	v_pk_mul_f32 v[220:221], v[212:213], v[128:129]
	v_pk_mul_f32 v[128:129], v[212:213], v[128:129] op_sel:[1,0] op_sel_hi:[0,1]
	v_pk_mul_f32 v[224:225], v[216:217], v[160:161]
	v_pk_mul_f32 v[160:161], v[216:217], v[160:161] op_sel:[1,0] op_sel_hi:[0,1]
	v_sub_f32_e32 v208, v208, v209
	v_add_f32_e32 v130, v130, v131
	v_add_f32_e32 v209, v206, v207
	v_sub_f32_e32 v131, v220, v221
	v_add_f32_e32 v128, v128, v129
	v_sub_f32_e32 v129, v222, v223
	v_sub_f32_e32 v220, v224, v225
	v_add_f32_e32 v160, v160, v161
	v_cvt_pk_bf16_f32 v206, v208, v130
	v_cvt_pk_bf16_f32 v207, v131, v128
	v_cvt_pk_bf16_f32 v208, v129, v209
	v_cvt_pk_bf16_f32 v209, v220, v160
	ds_read_b32 v130, v167
	v_lshl_add_u64 v[128:129], v[158:159], 1, v[218:219]
	v_lshlrev_b64 v[158:159], s10, v[148:149]
	v_lshl_add_u64 v[158:159], v[158:159], 1, v[128:129]
	v_cndmask_b32_e64 v218, v205, v228, s[6:7]
	s_waitcnt lgkmcnt(0)
	v_add_f32_e32 v130, v204, v130
	v_fmamk_f32 v130, v130, 0x3c800000, v188
	v_rsq_f32_e32 v130, v130
	global_store_dwordx4 v[158:159], v[206:209], off
	v_pk_mul_f32 v[116:117], v[116:117], v[130:131] op_sel_hi:[1,0]
	v_pk_mul_f32 v[114:115], v[114:115], v[130:131] op_sel_hi:[1,0]
	v_pk_mul_f32 v[112:113], v[112:113], v[130:131] op_sel_hi:[1,0]
	v_pk_mul_f32 v[118:119], v[118:119], v[130:131] op_sel_hi:[1,0]
	v_pk_mul_f32 v[116:117], v[122:123], v[116:117]
	v_pk_mul_f32 v[114:115], v[124:125], v[114:115]
	v_pk_mul_f32 v[112:113], v[126:127], v[112:113]
	v_pk_mul_f32 v[118:119], v[120:121], v[118:119]
	v_pk_mul_f32 v[130:131], v[210:211], v[116:117]
	v_pk_mul_f32 v[116:117], v[210:211], v[116:117] op_sel:[1,0] op_sel_hi:[0,1]
	v_pk_mul_f32 v[204:205], v[214:215], v[112:113]
	v_pk_mul_f32 v[112:113], v[214:215], v[112:113] op_sel:[1,0] op_sel_hi:[0,1]
	v_pk_mul_f32 v[206:207], v[216:217], v[114:115]
	v_pk_mul_f32 v[114:115], v[216:217], v[114:115] op_sel:[1,0] op_sel_hi:[0,1]
	v_pk_mul_f32 v[160:161], v[212:213], v[118:119]
	v_pk_mul_f32 v[118:119], v[212:213], v[118:119] op_sel:[1,0] op_sel_hi:[0,1]
	v_sub_f32_e32 v130, v130, v131
	v_add_f32_e32 v116, v116, v117
	v_add_f32_e32 v131, v112, v113
	v_add_f32_e32 v115, v114, v115
	v_cvt_pk_bf16_f32 v112, v130, v116
	v_sub_f32_e32 v117, v160, v161
	v_add_f32_e32 v118, v118, v119
	v_sub_f32_e32 v119, v204, v205
	v_sub_f32_e32 v149, v206, v207
	v_cvt_pk_bf16_f32 v113, v117, v118
	v_cvt_pk_bf16_f32 v114, v119, v131
	v_cvt_pk_bf16_f32 v115, v149, v115
	global_store_dwordx4 v[158:159], v[112:115], off offset:256
	v_bitop3_b32 v131, v148, s89, 32 bitop3:0xc8
	v_add_u32_e32 v149, 0xffff0020, v148
	v_lshl_or_b32 v112, v218, 4, v164
	v_ashrrev_i32_e32 v113, 31, v112
	v_lshl_add_u64 v[116:117], v[112:113], 3, s[40:41]
	global_load_dwordx4 v[112:115], v[116:117], off
	s_nop 0
	global_load_dwordx4 v[116:119], v[116:117], off offset:16
	ds_read_b32 v130, v168
	v_cndmask_b32_e32 v131, v149, v131, vcc
	v_and_b32_e32 v149, 47, v131
	v_cmp_gt_i32_e32 vcc, s77, v150
	s_waitcnt lgkmcnt(0)
	v_add_f32_e32 v130, v203, v130
	v_fmamk_f32 v130, v130, 0x3c800000, v188
	v_rsq_f32_e32 v130, v130
	v_ashrrev_i32_e32 v203, 6, v131
	v_pk_mul_f32 v[108:109], v[108:109], v[130:131] op_sel_hi:[1,0]
	v_pk_mul_f32 v[106:107], v[106:107], v[130:131] op_sel_hi:[1,0]
	v_pk_mul_f32 v[110:111], v[110:111], v[130:131] op_sel_hi:[1,0]
	v_pk_mul_f32 v[104:105], v[104:105], v[130:131] op_sel_hi:[1,0]
	v_pk_mul_f32 v[108:109], v[122:123], v[108:109]
	v_pk_mul_f32 v[106:107], v[124:125], v[106:107]
	v_pk_mul_f32 v[110:111], v[120:121], v[110:111]
	v_pk_mul_f32 v[104:105], v[126:127], v[104:105]
	s_waitcnt vmcnt(1)
; __device__ __forceinline__ unsigned cvt_pk_bf16(float lo, float hi) { unsigned r; asm volatile("v_cvt_pk_bf16_f32 %0, %1, %2" : "=v"(r) : "v"(lo), "v"(hi)); return r; }
; #define ropetab WSP(float, WS_ROPE)
;     __device__ __forceinline__ void operator()(f32x4 (&acc)[2][2][4][2], const Unit& u, int wr, int wc, int fr, int fq, PG8_LAS unsigned char* sp) const {
;     ...
;             const float* gp = (isq ? qgain : kgain) + 32 * (wc & 1) + 8 * fq; const float gs = isq ? qscale : 1.0f;
;             const f32x4 gl0 = *(const f32x4*)(gp) * gs, gl1 = *(const f32x4*)(gp + 4) * gs;
; #pragma unroll
;             for (int ai = 0; ai < 2; ++ai)
; #pragma unroll
;                 for (int m = 0; m < 4; ++m) { const int row = row0 + ai * HALF + m * 16;
;                     f32x4 cs0 = {1.f, 0.f, 1.f, 0.f}, cs1 = {1.f, 0.f, 1.f, 0.f};
;                     if (ROPE) { const int t = (row < 65536) ? (row & 2047) : (row - 65536); const int pos = (wc & 1) ? (t & 63) : (t >> 6);
;                         const float* tp = ropetab + (size_t)(pos * 16 + 4 * fq) * 2; cs0 = *(const f32x4*)(tp); cs1 = *(const f32x4*)(tp + 4); }
;                     bf16_t* rowp = base + (size_t)row * ldc + col0;
; #pragma unroll
;                     for (int bj = 0; bj < 2; ++bj) { const int idx = (ai * 4 + m) * 2 + bj;
;                         const float tot = part[idx] + xch[(wid ^ 1) * 256 + idx * 16 + fr]; const float rinv = __builtin_amdgcn_rsqf(tot * (1.0f / 64.0f) + EPI_EPS);
;                         f32x4 v0 = acc[ai][bj][m][0] * rinv * gl0, v1 = acc[ai][bj][m][1] * rinv * gl1;
;                         if (ROPE) { const f32x4 a = v0, b = v1;
;                             v0[0] = a[0] * cs0[0] - a[1] * cs0[1]; v0[1] = a[0] * cs0[1] + a[1] * cs0[0]; v0[2] = a[2] * cs0[2] - a[3] * cs0[3]; v0[3] = a[2] * cs0[3] + a[3] * cs0[2];
;                             v1[0] = b[0] * cs1[0] - b[1] * cs1[1]; v1[1] = b[0] * cs1[1] + b[1] * cs1[0]; v1[2] = b[2] * cs1[2] - b[3] * cs1[3]; v1[3] = b[2] * cs1[3] + b[3] * cs1[2]; }
;                         u32x4 w; w.x = cvt_pk_bf16(v0[0], v0[1]); w.y = cvt_pk_bf16(v0[2], v0[3]); w.z = cvt_pk_bf16(v1[0], v1[1]); w.w = cvt_pk_bf16(v1[2], v1[3]);
;                         *(u32x4*)(rowp + bj * HALF) = w; } }
	v_pk_mul_f32 v[130:131], v[112:113], v[108:109]
	s_waitcnt vmcnt(0)
	v_pk_mul_f32 v[204:205], v[118:119], v[106:107]
	v_pk_mul_f32 v[106:107], v[118:119], v[106:107] op_sel:[1,0] op_sel_hi:[0,1]
	v_pk_mul_f32 v[108:109], v[112:113], v[108:109] op_sel:[1,0] op_sel_hi:[0,1]
	v_pk_mul_f32 v[158:159], v[114:115], v[110:111]
	v_pk_mul_f32 v[110:111], v[114:115], v[110:111] op_sel:[1,0] op_sel_hi:[0,1]
	v_pk_mul_f32 v[160:161], v[116:117], v[104:105]
	v_pk_mul_f32 v[104:105], v[116:117], v[104:105] op_sel:[1,0] op_sel_hi:[0,1]
	v_sub_f32_e32 v130, v130, v131
	v_add_f32_e32 v107, v106, v107
	v_add_f32_e32 v108, v108, v109
	v_sub_f32_e32 v109, v158, v159
	v_add_f32_e32 v110, v110, v111
	v_sub_f32_e32 v111, v160, v161
	v_add_f32_e32 v131, v104, v105
	v_sub_f32_e32 v158, v204, v205
	v_cvt_pk_bf16_f32 v104, v130, v108
	v_cvt_pk_bf16_f32 v105, v109, v110
	v_cvt_pk_bf16_f32 v106, v111, v131
	v_cvt_pk_bf16_f32 v107, v158, v107
	ds_read_b32 v130, v169
	v_lshlrev_b64 v[110:111], s10, v[154:155]
	v_cndmask_b32_e64 v108, v149, v203, s[6:7]
	v_lshl_add_u64 v[110:111], v[110:111], 1, v[128:129]
	v_lshl_or_b32 v108, v108, 4, v164
	s_waitcnt lgkmcnt(0)
	v_add_f32_e32 v130, v202, v130
	v_fmamk_f32 v130, v130, 0x3c800000, v188
	v_rsq_f32_e32 v130, v130
	global_store_dwordx4 v[110:111], v[104:107], off
	v_ashrrev_i32_e32 v109, 31, v108
	v_lshl_add_u64 v[108:109], v[108:109], 3, s[40:41]
	global_load_dwordx4 v[232:235], v[108:109], off
	s_nop 0
	global_load_dwordx4 v[236:239], v[108:109], off offset:16
	v_pk_mul_f32 v[102:103], v[102:103], v[130:131] op_sel_hi:[1,0]
	v_pk_mul_f32 v[98:99], v[98:99], v[130:131] op_sel_hi:[1,0]
	v_pk_mul_f32 v[100:101], v[100:101], v[130:131] op_sel_hi:[1,0]
	v_pk_mul_f32 v[96:97], v[96:97], v[130:131] op_sel_hi:[1,0]
	v_pk_mul_f32 v[102:103], v[120:121], v[102:103]
	v_pk_mul_f32 v[98:99], v[124:125], v[98:99]
	v_pk_mul_f32 v[100:101], v[122:123], v[100:101]
	v_pk_mul_f32 v[96:97], v[126:127], v[96:97]
	v_pk_mul_f32 v[106:107], v[114:115], v[102:103]
	v_pk_mul_f32 v[102:103], v[114:115], v[102:103] op_sel:[1,0] op_sel_hi:[0,1]
	v_pk_mul_f32 v[114:115], v[118:119], v[98:99]
	v_pk_mul_f32 v[98:99], v[118:119], v[98:99] op_sel:[1,0] op_sel_hi:[0,1]
	v_pk_mul_f32 v[104:105], v[112:113], v[100:101]
	v_pk_mul_f32 v[100:101], v[112:113], v[100:101] op_sel:[1,0] op_sel_hi:[0,1]
	v_pk_mul_f32 v[112:113], v[116:117], v[96:97]
	v_pk_mul_f32 v[96:97], v[116:117], v[96:97] op_sel:[1,0] op_sel_hi:[0,1]
	v_add_f32_e32 v99, v98, v99
	v_sub_f32_e32 v104, v104, v105
	v_add_f32_e32 v100, v100, v101
	v_sub_f32_e32 v101, v106, v107
	v_add_f32_e32 v102, v102, v103
	v_sub_f32_e32 v103, v112, v113
	v_add_f32_e32 v105, v96, v97
	v_sub_f32_e32 v106, v114, v115
	v_cvt_pk_bf16_f32 v96, v104, v100
	v_cvt_pk_bf16_f32 v97, v101, v102
	v_cvt_pk_bf16_f32 v98, v103, v105
	v_cvt_pk_bf16_f32 v99, v106, v99
	global_store_dwordx4 v[110:111], v[96:99], off offset:256
	ds_read_b32 v104, v170
	v_bitop3_b32 v105, v148, s90, 48 bitop3:0xc8
	v_add_u32_e32 v106, 0xffff0030, v148
	v_cndmask_b32_e32 v105, v106, v105, vcc
	v_and_b32_e32 v112, 63, v105
	s_waitcnt lgkmcnt(0)
	v_add_f32_e32 v104, v201, v104
	v_fmamk_f32 v104, v104, 0x3c800000, v188
	v_rsq_f32_e32 v104, v104
	v_ashrrev_i32_e32 v113, 6, v105
	v_cmp_gt_i32_e32 vcc, s91, v148
	v_pk_mul_f32 v[92:93], v[92:93], v[104:105] op_sel_hi:[1,0]
	v_pk_mul_f32 v[90:91], v[90:91], v[104:105] op_sel_hi:[1,0]
	v_pk_mul_f32 v[94:95], v[94:95], v[104:105] op_sel_hi:[1,0]
	v_pk_mul_f32 v[88:89], v[88:89], v[104:105] op_sel_hi:[1,0]
	v_pk_mul_f32 v[92:93], v[122:123], v[92:93]
	v_pk_mul_f32 v[90:91], v[124:125], v[90:91]
	v_pk_mul_f32 v[94:95], v[120:121], v[94:95]
	v_pk_mul_f32 v[88:89], v[126:127], v[88:89]
	s_waitcnt vmcnt(2)
	v_pk_mul_f32 v[104:105], v[232:233], v[92:93]
	s_waitcnt vmcnt(1)
	v_pk_mul_f32 v[110:111], v[238:239], v[90:91]
	v_pk_mul_f32 v[90:91], v[238:239], v[90:91] op_sel:[1,0] op_sel_hi:[0,1]
	v_pk_mul_f32 v[92:93], v[232:233], v[92:93] op_sel:[1,0] op_sel_hi:[0,1]
	v_pk_mul_f32 v[106:107], v[234:235], v[94:95]
	v_pk_mul_f32 v[94:95], v[234:235], v[94:95] op_sel:[1,0] op_sel_hi:[0,1]
	v_pk_mul_f32 v[108:109], v[236:237], v[88:89]
	v_pk_mul_f32 v[88:89], v[236:237], v[88:89] op_sel:[1,0] op_sel_hi:[0,1]
	v_sub_f32_e32 v104, v104, v105
	v_add_f32_e32 v91, v90, v91
	v_add_f32_e32 v92, v92, v93
	v_sub_f32_e32 v93, v106, v107
	v_add_f32_e32 v94, v94, v95
	v_sub_f32_e32 v95, v108, v109
	v_add_f32_e32 v105, v88, v89
	v_sub_f32_e32 v106, v110, v111
	v_cvt_pk_bf16_f32 v88, v104, v92
	v_cvt_pk_bf16_f32 v89, v93, v94
	v_cvt_pk_bf16_f32 v90, v95, v105
	v_cvt_pk_bf16_f32 v91, v106, v91
	ds_read_b32 v104, v171
	v_lshlrev_b64 v[94:95], s10, v[152:153]
	v_cndmask_b32_e64 v92, v112, v113, s[6:7]
	v_lshl_add_u64 v[94:95], v[94:95], 1, v[128:129]
	v_lshl_or_b32 v92, v92, 4, v164
	s_waitcnt lgkmcnt(0)
; __device__ __forceinline__ unsigned cvt_pk_bf16(float lo, float hi) { unsigned r; asm volatile("v_cvt_pk_bf16_f32 %0, %1, %2" : "=v"(r) : "v"(lo), "v"(hi)); return r; }
; #define ropetab WSP(float, WS_ROPE)
;     __device__ __forceinline__ void operator()(f32x4 (&acc)[2][2][4][2], const Unit& u, int wr, int wc, int fr, int fq, PG8_LAS unsigned char* sp) const {
;     ...
;             const float* gp = (isq ? qgain : kgain) + 32 * (wc & 1) + 8 * fq; const float gs = isq ? qscale : 1.0f;
;             const f32x4 gl0 = *(const f32x4*)(gp) * gs, gl1 = *(const f32x4*)(gp + 4) * gs;
; #pragma unroll
;             for (int ai = 0; ai < 2; ++ai)
; #pragma unroll
;                 for (int m = 0; m < 4; ++m) { const int row = row0 + ai * HALF + m * 16;
;                     f32x4 cs0 = {1.f, 0.f, 1.f, 0.f}, cs1 = {1.f, 0.f, 1.f, 0.f};
;                     if (ROPE) { const int t = (row < 65536) ? (row & 2047) : (row - 65536); const int pos = (wc & 1) ? (t & 63) : (t >> 6);
;                         const float* tp = ropetab + (size_t)(pos * 16 + 4 * fq) * 2; cs0 = *(const f32x4*)(tp); cs1 = *(const f32x4*)(tp + 4); }
;                     bf16_t* rowp = base + (size_t)row * ldc + col0;
; #pragma unroll
;                     for (int bj = 0; bj < 2; ++bj) { const int idx = (ai * 4 + m) * 2 + bj;
;                         const float tot = part[idx] + xch[(wid ^ 1) * 256 + idx * 16 + fr]; const float rinv = __builtin_amdgcn_rsqf(tot * (1.0f / 64.0f) + EPI_EPS);
;                         f32x4 v0 = acc[ai][bj][m][0] * rinv * gl0, v1 = acc[ai][bj][m][1] * rinv * gl1;
;                         if (ROPE) { const f32x4 a = v0, b = v1;
;                             v0[0] = a[0] * cs0[0] - a[1] * cs0[1]; v0[1] = a[0] * cs0[1] + a[1] * cs0[0]; v0[2] = a[2] * cs0[2] - a[3] * cs0[3]; v0[3] = a[2] * cs0[3] + a[3] * cs0[2];
;                             v1[0] = b[0] * cs1[0] - b[1] * cs1[1]; v1[1] = b[0] * cs1[1] + b[1] * cs1[0]; v1[2] = b[2] * cs1[2] - b[3] * cs1[3]; v1[3] = b[2] * cs1[3] + b[3] * cs1[2]; }
;                         u32x4 w; w.x = cvt_pk_bf16(v0[0], v0[1]); w.y = cvt_pk_bf16(v0[2], v0[3]); w.z = cvt_pk_bf16(v1[0], v1[1]); w.w = cvt_pk_bf16(v1[2], v1[3]);
;                         *(u32x4*)(rowp + bj * HALF) = w; } }
	v_add_f32_e32 v104, v200, v104
	v_fmamk_f32 v104, v104, 0x3c800000, v188
	v_rsq_f32_e32 v104, v104
	global_store_dwordx4 v[94:95], v[88:91], off
	v_ashrrev_i32_e32 v93, 31, v92
	v_lshl_add_u64 v[92:93], v[92:93], 3, s[40:41]
	global_load_dwordx4 v[240:243], v[92:93], off
	s_nop 0
	global_load_dwordx4 v[244:247], v[92:93], off offset:16
	v_pk_mul_f32 v[86:87], v[86:87], v[104:105] op_sel_hi:[1,0]
	v_pk_mul_f32 v[82:83], v[82:83], v[104:105] op_sel_hi:[1,0]
	v_pk_mul_f32 v[84:85], v[84:85], v[104:105] op_sel_hi:[1,0]
	v_pk_mul_f32 v[80:81], v[80:81], v[104:105] op_sel_hi:[1,0]
	v_pk_mul_f32 v[86:87], v[120:121], v[86:87]
	v_pk_mul_f32 v[82:83], v[124:125], v[82:83]
	v_pk_mul_f32 v[84:85], v[122:123], v[84:85]
	v_pk_mul_f32 v[80:81], v[126:127], v[80:81]
	v_pk_mul_f32 v[90:91], v[234:235], v[86:87]
	v_pk_mul_f32 v[86:87], v[234:235], v[86:87] op_sel:[1,0] op_sel_hi:[0,1]
	v_pk_mul_f32 v[98:99], v[238:239], v[82:83]
	v_pk_mul_f32 v[82:83], v[238:239], v[82:83] op_sel:[1,0] op_sel_hi:[0,1]
	v_pk_mul_f32 v[88:89], v[232:233], v[84:85]
	v_pk_mul_f32 v[84:85], v[232:233], v[84:85] op_sel:[1,0] op_sel_hi:[0,1]
	v_pk_mul_f32 v[96:97], v[236:237], v[80:81]
	v_pk_mul_f32 v[80:81], v[236:237], v[80:81] op_sel:[1,0] op_sel_hi:[0,1]
	v_add_f32_e32 v83, v82, v83
	v_sub_f32_e32 v88, v88, v89
	v_add_f32_e32 v84, v84, v85
	v_sub_f32_e32 v85, v90, v91
	v_add_f32_e32 v86, v86, v87
	v_sub_f32_e32 v87, v96, v97
	v_add_f32_e32 v89, v80, v81
	v_sub_f32_e32 v90, v98, v99
	v_cvt_pk_bf16_f32 v80, v88, v84
	v_cvt_pk_bf16_f32 v81, v85, v86
	v_cvt_pk_bf16_f32 v82, v87, v89
	v_cvt_pk_bf16_f32 v83, v90, v83
	global_store_dwordx4 v[94:95], v[80:83], off offset:256
	ds_read_b32 v89, v172
	v_add_u32_e32 v91, 0xffff0080, v148
	v_add_u32_e32 v88, 0x80, v148
	v_and_b32_e32 v92, 0x7cf, v88
	s_waitcnt lgkmcnt(0)
	v_add_f32_e32 v89, v199, v89
	v_fmamk_f32 v89, v89, 0x3c800000, v188
	v_rsq_f32_e32 v90, v89
	v_cndmask_b32_e32 v89, v91, v92, vcc
	v_and_b32_e32 v98, 15, v89
	v_ashrrev_i32_e32 v89, 6, v89
	v_pk_mul_f32 v[76:77], v[76:77], v[90:91] op_sel_hi:[1,0]
	v_pk_mul_f32 v[74:75], v[74:75], v[90:91] op_sel_hi:[1,0]
	v_pk_mul_f32 v[78:79], v[78:79], v[90:91] op_sel_hi:[1,0]
	v_pk_mul_f32 v[72:73], v[72:73], v[90:91] op_sel_hi:[1,0]
	v_pk_mul_f32 v[76:77], v[122:123], v[76:77]
	v_pk_mul_f32 v[74:75], v[124:125], v[74:75]
	v_pk_mul_f32 v[78:79], v[120:121], v[78:79]
	v_pk_mul_f32 v[72:73], v[126:127], v[72:73]
	v_cmp_gt_i32_e32 vcc, s92, v148
	s_waitcnt vmcnt(2)
	v_pk_mul_f32 v[90:91], v[240:241], v[76:77]
	s_waitcnt vmcnt(1)
	v_pk_mul_f32 v[96:97], v[246:247], v[74:75]
	v_pk_mul_f32 v[74:75], v[246:247], v[74:75] op_sel:[1,0] op_sel_hi:[0,1]
	v_pk_mul_f32 v[76:77], v[240:241], v[76:77] op_sel:[1,0] op_sel_hi:[0,1]
	v_pk_mul_f32 v[92:93], v[242:243], v[78:79]
	v_pk_mul_f32 v[78:79], v[242:243], v[78:79] op_sel:[1,0] op_sel_hi:[0,1]
	v_pk_mul_f32 v[94:95], v[244:245], v[72:73]
	v_pk_mul_f32 v[72:73], v[244:245], v[72:73] op_sel:[1,0] op_sel_hi:[0,1]
	v_sub_f32_e32 v90, v90, v91
	v_add_f32_e32 v75, v74, v75
	v_add_f32_e32 v76, v76, v77
	v_sub_f32_e32 v77, v92, v93
	v_add_f32_e32 v78, v78, v79
	v_sub_f32_e32 v79, v94, v95
	v_add_f32_e32 v91, v72, v73
	v_sub_f32_e32 v92, v96, v97
	v_cvt_pk_bf16_f32 v72, v90, v76
	v_cvt_pk_bf16_f32 v73, v77, v78
	v_cvt_pk_bf16_f32 v74, v79, v91
	v_cvt_pk_bf16_f32 v75, v92, v75
	ds_read_b32 v90, v173
	v_cndmask_b32_e64 v76, v98, v89, s[6:7]
	v_lshlrev_b64 v[78:79], s10, v[150:151]
	v_lshl_add_u64 v[78:79], v[78:79], 1, v[128:129]
	v_lshl_or_b32 v76, v76, 4, v164
	s_waitcnt lgkmcnt(0)
	v_add_f32_e32 v89, v198, v90
	v_fmamk_f32 v89, v89, 0x3c800000, v188
	v_rsq_f32_e32 v90, v89
	global_store_dwordx4 v[78:79], v[72:75], off
	v_ashrrev_i32_e32 v77, 31, v76
	v_lshl_add_u64 v[76:77], v[76:77], 3, s[40:41]
	global_load_dwordx4 v[232:235], v[76:77], off
	s_nop 0
	global_load_dwordx4 v[236:239], v[76:77], off offset:16
	v_pk_mul_f32 v[70:71], v[70:71], v[90:91] op_sel_hi:[1,0]
	v_pk_mul_f32 v[66:67], v[66:67], v[90:91] op_sel_hi:[1,0]
	v_pk_mul_f32 v[68:69], v[68:69], v[90:91] op_sel_hi:[1,0]
	v_pk_mul_f32 v[64:65], v[64:65], v[90:91] op_sel_hi:[1,0]
	v_pk_mul_f32 v[70:71], v[120:121], v[70:71]
	v_pk_mul_f32 v[66:67], v[124:125], v[66:67]
	v_pk_mul_f32 v[68:69], v[122:123], v[68:69]
	v_pk_mul_f32 v[64:65], v[126:127], v[64:65]
	v_pk_mul_f32 v[74:75], v[242:243], v[70:71]
	v_pk_mul_f32 v[70:71], v[242:243], v[70:71] op_sel:[1,0] op_sel_hi:[0,1]
	v_pk_mul_f32 v[82:83], v[246:247], v[66:67]
	v_pk_mul_f32 v[66:67], v[246:247], v[66:67] op_sel:[1,0] op_sel_hi:[0,1]
	v_pk_mul_f32 v[72:73], v[240:241], v[68:69]
	v_pk_mul_f32 v[68:69], v[240:241], v[68:69] op_sel:[1,0] op_sel_hi:[0,1]
	v_pk_mul_f32 v[80:81], v[244:245], v[64:65]
	v_pk_mul_f32 v[64:65], v[244:245], v[64:65] op_sel:[1,0] op_sel_hi:[0,1]
	v_add_f32_e32 v67, v66, v67
	v_sub_f32_e32 v72, v72, v73
	v_add_f32_e32 v68, v68, v69
	v_sub_f32_e32 v69, v74, v75
	v_add_f32_e32 v70, v70, v71
	v_sub_f32_e32 v71, v80, v81
	v_add_f32_e32 v73, v64, v65
	v_sub_f32_e32 v74, v82, v83
	v_cvt_pk_bf16_f32 v64, v72, v68
	v_cvt_pk_bf16_f32 v65, v69, v70
	v_cvt_pk_bf16_f32 v66, v71, v73
	v_cvt_pk_bf16_f32 v67, v74, v67
	global_store_dwordx4 v[78:79], v[64:67], off offset:256
	ds_read_b32 v73, v174
	v_add_u32_e32 v75, 0xffff0090, v148
	v_add_u32_e32 v72, 0x90, v148
	v_and_b32_e32 v76, 0x7df, v72
	v_ashrrev_i32_e32 v89, 31, v88
	s_waitcnt lgkmcnt(0)
; __device__ __forceinline__ unsigned cvt_pk_bf16(float lo, float hi) { unsigned r; asm volatile("v_cvt_pk_bf16_f32 %0, %1, %2" : "=v"(r) : "v"(lo), "v"(hi)); return r; }
; #define ropetab WSP(float, WS_ROPE)
;     __device__ __forceinline__ void operator()(f32x4 (&acc)[2][2][4][2], const Unit& u, int wr, int wc, int fr, int fq, PG8_LAS unsigned char* sp) const {
;     ...
;             const float* gp = (isq ? qgain : kgain) + 32 * (wc & 1) + 8 * fq; const float gs = isq ? qscale : 1.0f;
;             const f32x4 gl0 = *(const f32x4*)(gp) * gs, gl1 = *(const f32x4*)(gp + 4) * gs;
; #pragma unroll
;             for (int ai = 0; ai < 2; ++ai)
; #pragma unroll
;                 for (int m = 0; m < 4; ++m) { const int row = row0 + ai * HALF + m * 16;
;                     f32x4 cs0 = {1.f, 0.f, 1.f, 0.f}, cs1 = {1.f, 0.f, 1.f, 0.f};
;                     if (ROPE) { const int t = (row < 65536) ? (row & 2047) : (row - 65536); const int pos = (wc & 1) ? (t & 63) : (t >> 6);
;                         const float* tp = ropetab + (size_t)(pos * 16 + 4 * fq) * 2; cs0 = *(const f32x4*)(tp); cs1 = *(const f32x4*)(tp + 4); }
;                     bf16_t* rowp = base + (size_t)row * ldc + col0;
; #pragma unroll
;                     for (int bj = 0; bj < 2; ++bj) { const int idx = (ai * 4 + m) * 2 + bj;
;                         const float tot = part[idx] + xch[(wid ^ 1) * 256 + idx * 16 + fr]; const float rinv = __builtin_amdgcn_rsqf(tot * (1.0f / 64.0f) + EPI_EPS);
;                         f32x4 v0 = acc[ai][bj][m][0] * rinv * gl0, v1 = acc[ai][bj][m][1] * rinv * gl1;
;                         if (ROPE) { const f32x4 a = v0, b = v1;
;                             v0[0] = a[0] * cs0[0] - a[1] * cs0[1]; v0[1] = a[0] * cs0[1] + a[1] * cs0[0]; v0[2] = a[2] * cs0[2] - a[3] * cs0[3]; v0[3] = a[2] * cs0[3] + a[3] * cs0[2];
;                             v1[0] = b[0] * cs1[0] - b[1] * cs1[1]; v1[1] = b[0] * cs1[1] + b[1] * cs1[0]; v1[2] = b[2] * cs1[2] - b[3] * cs1[3]; v1[3] = b[2] * cs1[3] + b[3] * cs1[2]; }
;                         u32x4 w; w.x = cvt_pk_bf16(v0[0], v0[1]); w.y = cvt_pk_bf16(v0[2], v0[3]); w.z = cvt_pk_bf16(v1[0], v1[1]); w.w = cvt_pk_bf16(v1[2], v1[3]);
;                         *(u32x4*)(rowp + bj * HALF) = w; } }
	v_add_f32_e32 v73, v197, v73
	v_fmamk_f32 v73, v73, 0x3c800000, v188
	v_rsq_f32_e32 v74, v73
	v_cndmask_b32_e32 v73, v75, v76, vcc
	v_and_b32_e32 v82, 31, v73
	v_ashrrev_i32_e32 v73, 6, v73
	v_pk_mul_f32 v[60:61], v[60:61], v[74:75] op_sel_hi:[1,0]
	v_pk_mul_f32 v[58:59], v[58:59], v[74:75] op_sel_hi:[1,0]
	v_pk_mul_f32 v[62:63], v[62:63], v[74:75] op_sel_hi:[1,0]
	v_pk_mul_f32 v[56:57], v[56:57], v[74:75] op_sel_hi:[1,0]
	v_pk_mul_f32 v[60:61], v[122:123], v[60:61]
	v_pk_mul_f32 v[58:59], v[124:125], v[58:59]
	v_pk_mul_f32 v[62:63], v[120:121], v[62:63]
	v_pk_mul_f32 v[56:57], v[126:127], v[56:57]
	v_cmp_gt_i32_e32 vcc, s93, v148
	s_waitcnt vmcnt(2)
	v_pk_mul_f32 v[74:75], v[232:233], v[60:61]
	s_waitcnt vmcnt(1)
	v_pk_mul_f32 v[80:81], v[238:239], v[58:59]
	v_pk_mul_f32 v[58:59], v[238:239], v[58:59] op_sel:[1,0] op_sel_hi:[0,1]
	v_pk_mul_f32 v[60:61], v[232:233], v[60:61] op_sel:[1,0] op_sel_hi:[0,1]
	v_pk_mul_f32 v[76:77], v[234:235], v[62:63]
	v_pk_mul_f32 v[62:63], v[234:235], v[62:63] op_sel:[1,0] op_sel_hi:[0,1]
	v_pk_mul_f32 v[78:79], v[236:237], v[56:57]
	v_pk_mul_f32 v[56:57], v[236:237], v[56:57] op_sel:[1,0] op_sel_hi:[0,1]
	v_sub_f32_e32 v74, v74, v75
	v_add_f32_e32 v59, v58, v59
	v_add_f32_e32 v60, v60, v61
	v_sub_f32_e32 v61, v76, v77
	v_add_f32_e32 v62, v62, v63
	v_sub_f32_e32 v63, v78, v79
	v_add_f32_e32 v75, v56, v57
	v_sub_f32_e32 v76, v80, v81
	v_cvt_pk_bf16_f32 v56, v74, v60
	v_cvt_pk_bf16_f32 v57, v61, v62
	v_cvt_pk_bf16_f32 v58, v63, v75
	v_cvt_pk_bf16_f32 v59, v76, v59
	ds_read_b32 v74, v175
	v_cndmask_b32_e64 v60, v82, v73, s[6:7]
	v_lshlrev_b64 v[62:63], s10, v[88:89]
	v_lshl_add_u64 v[62:63], v[62:63], 1, v[128:129]
	v_lshl_or_b32 v60, v60, 4, v164
	s_waitcnt lgkmcnt(0)
	v_add_f32_e32 v73, v196, v74
	v_fmamk_f32 v73, v73, 0x3c800000, v188
	v_rsq_f32_e32 v74, v73
	global_store_dwordx4 v[62:63], v[56:59], off
	v_ashrrev_i32_e32 v61, 31, v60
	v_lshl_add_u64 v[60:61], v[60:61], 3, s[40:41]
	global_load_dwordx4 v[240:243], v[60:61], off
	s_nop 0
	global_load_dwordx4 v[244:247], v[60:61], off offset:16
	v_pk_mul_f32 v[54:55], v[54:55], v[74:75] op_sel_hi:[1,0]
	v_pk_mul_f32 v[50:51], v[50:51], v[74:75] op_sel_hi:[1,0]
	v_pk_mul_f32 v[52:53], v[52:53], v[74:75] op_sel_hi:[1,0]
	v_pk_mul_f32 v[48:49], v[48:49], v[74:75] op_sel_hi:[1,0]
	v_pk_mul_f32 v[54:55], v[120:121], v[54:55]
	v_pk_mul_f32 v[50:51], v[124:125], v[50:51]
	v_pk_mul_f32 v[52:53], v[122:123], v[52:53]
	v_pk_mul_f32 v[48:49], v[126:127], v[48:49]
	v_pk_mul_f32 v[58:59], v[234:235], v[54:55]
	v_pk_mul_f32 v[54:55], v[234:235], v[54:55] op_sel:[1,0] op_sel_hi:[0,1]
	v_pk_mul_f32 v[66:67], v[238:239], v[50:51]
	v_pk_mul_f32 v[50:51], v[238:239], v[50:51] op_sel:[1,0] op_sel_hi:[0,1]
	v_pk_mul_f32 v[56:57], v[232:233], v[52:53]
	v_pk_mul_f32 v[52:53], v[232:233], v[52:53] op_sel:[1,0] op_sel_hi:[0,1]
	v_pk_mul_f32 v[64:65], v[236:237], v[48:49]
	v_pk_mul_f32 v[48:49], v[236:237], v[48:49] op_sel:[1,0] op_sel_hi:[0,1]
	v_add_f32_e32 v51, v50, v51
	v_sub_f32_e32 v56, v56, v57
	v_add_f32_e32 v52, v52, v53
	v_sub_f32_e32 v53, v58, v59
	v_add_f32_e32 v54, v54, v55
	v_sub_f32_e32 v55, v64, v65
	v_add_f32_e32 v57, v48, v49
	v_sub_f32_e32 v58, v66, v67
	v_cvt_pk_bf16_f32 v48, v56, v52
	v_cvt_pk_bf16_f32 v49, v53, v54
	v_cvt_pk_bf16_f32 v50, v55, v57
	v_cvt_pk_bf16_f32 v51, v58, v51
	global_store_dwordx4 v[62:63], v[48:51], off offset:256
	ds_read_b32 v57, v176
	v_add_u32_e32 v59, 0xffff00a0, v148
	v_add_u32_e32 v56, 0xa0, v148
	v_and_b32_e32 v60, 0x7ef, v56
	v_ashrrev_i32_e32 v73, 31, v72
	s_waitcnt lgkmcnt(0)
	v_add_f32_e32 v57, v195, v57
	v_fmamk_f32 v57, v57, 0x3c800000, v188
	v_rsq_f32_e32 v58, v57
	v_cndmask_b32_e32 v57, v59, v60, vcc
	v_and_b32_e32 v66, 47, v57
	v_ashrrev_i32_e32 v57, 6, v57
	v_pk_mul_f32 v[44:45], v[44:45], v[58:59] op_sel_hi:[1,0]
	v_pk_mul_f32 v[42:43], v[42:43], v[58:59] op_sel_hi:[1,0]
	v_pk_mul_f32 v[46:47], v[46:47], v[58:59] op_sel_hi:[1,0]
	v_pk_mul_f32 v[40:41], v[40:41], v[58:59] op_sel_hi:[1,0]
	v_pk_mul_f32 v[44:45], v[122:123], v[44:45]
	v_pk_mul_f32 v[42:43], v[124:125], v[42:43]
	v_pk_mul_f32 v[46:47], v[120:121], v[46:47]
	v_pk_mul_f32 v[40:41], v[126:127], v[40:41]
	v_cmp_gt_i32_e32 vcc, s94, v148
	s_waitcnt vmcnt(2)
	v_pk_mul_f32 v[58:59], v[240:241], v[44:45]
	s_waitcnt vmcnt(1)
	v_pk_mul_f32 v[64:65], v[246:247], v[42:43]
	v_pk_mul_f32 v[42:43], v[246:247], v[42:43] op_sel:[1,0] op_sel_hi:[0,1]
	v_pk_mul_f32 v[44:45], v[240:241], v[44:45] op_sel:[1,0] op_sel_hi:[0,1]
	v_pk_mul_f32 v[60:61], v[242:243], v[46:47]
	v_pk_mul_f32 v[46:47], v[242:243], v[46:47] op_sel:[1,0] op_sel_hi:[0,1]
	v_pk_mul_f32 v[62:63], v[244:245], v[40:41]
	v_pk_mul_f32 v[40:41], v[244:245], v[40:41] op_sel:[1,0] op_sel_hi:[0,1]
	v_sub_f32_e32 v58, v58, v59
	v_add_f32_e32 v43, v42, v43
	v_add_f32_e32 v44, v44, v45
	v_sub_f32_e32 v45, v60, v61
	v_add_f32_e32 v46, v46, v47
	v_sub_f32_e32 v47, v62, v63
	v_add_f32_e32 v59, v40, v41
	v_sub_f32_e32 v60, v64, v65
	v_cvt_pk_bf16_f32 v40, v58, v44
	v_cvt_pk_bf16_f32 v41, v45, v46
	v_cvt_pk_bf16_f32 v42, v47, v59
	v_cvt_pk_bf16_f32 v43, v60, v43
	ds_read_b32 v58, v177
	v_cndmask_b32_e64 v44, v66, v57, s[6:7]
	v_lshlrev_b64 v[46:47], s10, v[72:73]
	v_lshl_add_u64 v[46:47], v[46:47], 1, v[128:129]
	v_lshl_or_b32 v44, v44, 4, v164
	s_waitcnt lgkmcnt(0)
; __device__ __forceinline__ unsigned cvt_pk_bf16(float lo, float hi) { unsigned r; asm volatile("v_cvt_pk_bf16_f32 %0, %1, %2" : "=v"(r) : "v"(lo), "v"(hi)); return r; }
; #define ropetab WSP(float, WS_ROPE)
;     __device__ __forceinline__ void operator()(f32x4 (&acc)[2][2][4][2], const Unit& u, int wr, int wc, int fr, int fq, PG8_LAS unsigned char* sp) const {
;     ...
;             const float* gp = (isq ? qgain : kgain) + 32 * (wc & 1) + 8 * fq; const float gs = isq ? qscale : 1.0f;
;             const f32x4 gl0 = *(const f32x4*)(gp) * gs, gl1 = *(const f32x4*)(gp + 4) * gs;
; #pragma unroll
;             for (int ai = 0; ai < 2; ++ai)
; #pragma unroll
;                 for (int m = 0; m < 4; ++m) { const int row = row0 + ai * HALF + m * 16;
;                     f32x4 cs0 = {1.f, 0.f, 1.f, 0.f}, cs1 = {1.f, 0.f, 1.f, 0.f};
;                     if (ROPE) { const int t = (row < 65536) ? (row & 2047) : (row - 65536); const int pos = (wc & 1) ? (t & 63) : (t >> 6);
;                         const float* tp = ropetab + (size_t)(pos * 16 + 4 * fq) * 2; cs0 = *(const f32x4*)(tp); cs1 = *(const f32x4*)(tp + 4); }
;                     bf16_t* rowp = base + (size_t)row * ldc + col0;
; #pragma unroll
;                     for (int bj = 0; bj < 2; ++bj) { const int idx = (ai * 4 + m) * 2 + bj;
;                         const float tot = part[idx] + xch[(wid ^ 1) * 256 + idx * 16 + fr]; const float rinv = __builtin_amdgcn_rsqf(tot * (1.0f / 64.0f) + EPI_EPS);
;                         f32x4 v0 = acc[ai][bj][m][0] * rinv * gl0, v1 = acc[ai][bj][m][1] * rinv * gl1;
;                         if (ROPE) { const f32x4 a = v0, b = v1;
;                             v0[0] = a[0] * cs0[0] - a[1] * cs0[1]; v0[1] = a[0] * cs0[1] + a[1] * cs0[0]; v0[2] = a[2] * cs0[2] - a[3] * cs0[3]; v0[3] = a[2] * cs0[3] + a[3] * cs0[2];
;                             v1[0] = b[0] * cs1[0] - b[1] * cs1[1]; v1[1] = b[0] * cs1[1] + b[1] * cs1[0]; v1[2] = b[2] * cs1[2] - b[3] * cs1[3]; v1[3] = b[2] * cs1[3] + b[3] * cs1[2]; }
;                         u32x4 w; w.x = cvt_pk_bf16(v0[0], v0[1]); w.y = cvt_pk_bf16(v0[2], v0[3]); w.z = cvt_pk_bf16(v1[0], v1[1]); w.w = cvt_pk_bf16(v1[2], v1[3]);
;                         *(u32x4*)(rowp + bj * HALF) = w; } }
	v_add_f32_e32 v57, v194, v58
	v_fmamk_f32 v57, v57, 0x3c800000, v188
	v_rsq_f32_e32 v58, v57
	global_store_dwordx4 v[46:47], v[40:43], off
	v_ashrrev_i32_e32 v45, 31, v44
	v_lshl_add_u64 v[44:45], v[44:45], 3, s[40:41]
	global_load_dwordx4 v[232:235], v[44:45], off
	s_nop 0
	global_load_dwordx4 v[236:239], v[44:45], off offset:16
	v_pk_mul_f32 v[38:39], v[38:39], v[58:59] op_sel_hi:[1,0]
	v_pk_mul_f32 v[34:35], v[34:35], v[58:59] op_sel_hi:[1,0]
	v_pk_mul_f32 v[36:37], v[36:37], v[58:59] op_sel_hi:[1,0]
	v_pk_mul_f32 v[32:33], v[32:33], v[58:59] op_sel_hi:[1,0]
	v_pk_mul_f32 v[38:39], v[120:121], v[38:39]
	v_pk_mul_f32 v[34:35], v[124:125], v[34:35]
	v_pk_mul_f32 v[36:37], v[122:123], v[36:37]
	v_pk_mul_f32 v[32:33], v[126:127], v[32:33]
	v_pk_mul_f32 v[42:43], v[242:243], v[38:39]
	v_pk_mul_f32 v[38:39], v[242:243], v[38:39] op_sel:[1,0] op_sel_hi:[0,1]
	v_pk_mul_f32 v[50:51], v[246:247], v[34:35]
	v_pk_mul_f32 v[34:35], v[246:247], v[34:35] op_sel:[1,0] op_sel_hi:[0,1]
	v_pk_mul_f32 v[40:41], v[240:241], v[36:37]
	v_pk_mul_f32 v[36:37], v[240:241], v[36:37] op_sel:[1,0] op_sel_hi:[0,1]
	v_pk_mul_f32 v[48:49], v[244:245], v[32:33]
	v_pk_mul_f32 v[32:33], v[244:245], v[32:33] op_sel:[1,0] op_sel_hi:[0,1]
	v_add_f32_e32 v35, v34, v35
	v_sub_f32_e32 v40, v40, v41
	v_add_f32_e32 v36, v36, v37
	v_sub_f32_e32 v37, v42, v43
	v_add_f32_e32 v38, v38, v39
	v_sub_f32_e32 v39, v48, v49
	v_add_f32_e32 v41, v32, v33
	v_sub_f32_e32 v42, v50, v51
	v_cvt_pk_bf16_f32 v32, v40, v36
	v_cvt_pk_bf16_f32 v33, v37, v38
	v_cvt_pk_bf16_f32 v34, v39, v41
	v_cvt_pk_bf16_f32 v35, v42, v35
	global_store_dwordx4 v[46:47], v[32:35], off offset:256
	ds_read_b32 v41, v178
	v_add_u32_e32 v43, 0xffff00b0, v148
	v_add_u32_e32 v40, 0xb0, v148
	v_and_b32_e32 v44, 0x7ff, v40
	v_ashrrev_i32_e32 v57, 31, v56
	s_waitcnt lgkmcnt(0)
	v_add_f32_e32 v41, v193, v41
	v_fmamk_f32 v41, v41, 0x3c800000, v188
	v_rsq_f32_e32 v42, v41
	v_cndmask_b32_e32 v41, v43, v44, vcc
	v_and_b32_e32 v50, 63, v41
	v_ashrrev_i32_e32 v41, 6, v41
	v_pk_mul_f32 v[28:29], v[28:29], v[42:43] op_sel_hi:[1,0]
	v_pk_mul_f32 v[26:27], v[26:27], v[42:43] op_sel_hi:[1,0]
	v_pk_mul_f32 v[30:31], v[30:31], v[42:43] op_sel_hi:[1,0]
	v_pk_mul_f32 v[24:25], v[24:25], v[42:43] op_sel_hi:[1,0]
	v_pk_mul_f32 v[28:29], v[122:123], v[28:29]
	v_pk_mul_f32 v[26:27], v[124:125], v[26:27]
	v_pk_mul_f32 v[30:31], v[120:121], v[30:31]
	v_pk_mul_f32 v[24:25], v[126:127], v[24:25]
	s_waitcnt vmcnt(2)
	v_pk_mul_f32 v[42:43], v[232:233], v[28:29]
	s_waitcnt vmcnt(1)
	v_pk_mul_f32 v[48:49], v[238:239], v[26:27]
	v_pk_mul_f32 v[26:27], v[238:239], v[26:27] op_sel:[1,0] op_sel_hi:[0,1]
	v_pk_mul_f32 v[28:29], v[232:233], v[28:29] op_sel:[1,0] op_sel_hi:[0,1]
	v_pk_mul_f32 v[44:45], v[234:235], v[30:31]
	v_pk_mul_f32 v[30:31], v[234:235], v[30:31] op_sel:[1,0] op_sel_hi:[0,1]
	v_pk_mul_f32 v[46:47], v[236:237], v[24:25]
	v_pk_mul_f32 v[24:25], v[236:237], v[24:25] op_sel:[1,0] op_sel_hi:[0,1]
	v_sub_f32_e32 v42, v42, v43
	v_add_f32_e32 v27, v26, v27
	v_add_f32_e32 v28, v28, v29
	v_sub_f32_e32 v29, v44, v45
	v_add_f32_e32 v30, v30, v31
	v_sub_f32_e32 v31, v46, v47
	v_add_f32_e32 v43, v24, v25
	v_sub_f32_e32 v44, v48, v49
	v_cvt_pk_bf16_f32 v24, v42, v28
	v_cvt_pk_bf16_f32 v25, v29, v30
	v_cvt_pk_bf16_f32 v26, v31, v43
	v_cvt_pk_bf16_f32 v27, v44, v27
	ds_read_b32 v42, v179
	v_cndmask_b32_e64 v28, v50, v41, s[6:7]
	v_lshlrev_b64 v[30:31], s10, v[56:57]
	v_lshl_add_u64 v[30:31], v[30:31], 1, v[128:129]
	v_lshl_or_b32 v28, v28, 4, v164
	s_waitcnt lgkmcnt(0)
; __device__ __forceinline__ unsigned cvt_pk_bf16(float lo, float hi) { unsigned r; asm volatile("v_cvt_pk_bf16_f32 %0, %1, %2" : "=v"(r) : "v"(lo), "v"(hi)); return r; }
; #define ropetab WSP(float, WS_ROPE)
;     __device__ __forceinline__ void operator()(f32x4 (&acc)[2][2][4][2], const Unit& u, int wr, int wc, int fr, int fq, PG8_LAS unsigned char* sp) const {
;     ...
;                 for (int m = 0; m < 4; ++m) { const int row = row0 + ai * HALF + m * 16;
;                     f32x4 cs0 = {1.f, 0.f, 1.f, 0.f}, cs1 = {1.f, 0.f, 1.f, 0.f};
;                     if (ROPE) { const int t = (row < 65536) ? (row & 2047) : (row - 65536); const int pos = (wc & 1) ? (t & 63) : (t >> 6);
;                         const float* tp = ropetab + (size_t)(pos * 16 + 4 * fq) * 2; cs0 = *(const f32x4*)(tp); cs1 = *(const f32x4*)(tp + 4); }
;                     bf16_t* rowp = base + (size_t)row * ldc + col0;
; #pragma unroll
;                     for (int bj = 0; bj < 2; ++bj) { const int idx = (ai * 4 + m) * 2 + bj;
;                         const float tot = part[idx] + xch[(wid ^ 1) * 256 + idx * 16 + fr]; const float rinv = __builtin_amdgcn_rsqf(tot * (1.0f / 64.0f) + EPI_EPS);
;                         f32x4 v0 = acc[ai][bj][m][0] * rinv * gl0, v1 = acc[ai][bj][m][1] * rinv * gl1;
;                         if (ROPE) { const f32x4 a = v0, b = v1;
;                             v0[0] = a[0] * cs0[0] - a[1] * cs0[1]; v0[1] = a[0] * cs0[1] + a[1] * cs0[0]; v0[2] = a[2] * cs0[2] - a[3] * cs0[3]; v0[3] = a[2] * cs0[3] + a[3] * cs0[2];
;                             v1[0] = b[0] * cs1[0] - b[1] * cs1[1]; v1[1] = b[0] * cs1[1] + b[1] * cs1[0]; v1[2] = b[2] * cs1[2] - b[3] * cs1[3]; v1[3] = b[2] * cs1[3] + b[3] * cs1[2]; }
;                         u32x4 w; w.x = cvt_pk_bf16(v0[0], v0[1]); w.y = cvt_pk_bf16(v0[2], v0[3]); w.z = cvt_pk_bf16(v1[0], v1[1]); w.w = cvt_pk_bf16(v1[2], v1[3]);
;                         *(u32x4*)(rowp + bj * HALF) = w; } }
	v_add_f32_e32 v41, v192, v42
	v_fmamk_f32 v41, v41, 0x3c800000, v188
	v_rsq_f32_e32 v42, v41
	global_store_dwordx4 v[30:31], v[24:27], off
	v_ashrrev_i32_e32 v29, 31, v28
	v_lshl_add_u64 v[28:29], v[28:29], 3, s[40:41]
	global_load_dwordx4 v[240:243], v[28:29], off
	s_nop 0
	global_load_dwordx4 v[244:247], v[28:29], off offset:16
	v_pk_mul_f32 v[22:23], v[22:23], v[42:43] op_sel_hi:[1,0]
	v_pk_mul_f32 v[18:19], v[18:19], v[42:43] op_sel_hi:[1,0]
	v_pk_mul_f32 v[20:21], v[20:21], v[42:43] op_sel_hi:[1,0]
	v_pk_mul_f32 v[16:17], v[16:17], v[42:43] op_sel_hi:[1,0]
	v_pk_mul_f32 v[22:23], v[120:121], v[22:23]
	v_pk_mul_f32 v[18:19], v[124:125], v[18:19]
	v_pk_mul_f32 v[20:21], v[122:123], v[20:21]
	v_pk_mul_f32 v[16:17], v[126:127], v[16:17]
	v_pk_mul_f32 v[26:27], v[234:235], v[22:23]
	v_pk_mul_f32 v[22:23], v[234:235], v[22:23] op_sel:[1,0] op_sel_hi:[0,1]
	v_pk_mul_f32 v[34:35], v[238:239], v[18:19]
	v_pk_mul_f32 v[18:19], v[238:239], v[18:19] op_sel:[1,0] op_sel_hi:[0,1]
	v_pk_mul_f32 v[24:25], v[232:233], v[20:21]
	v_pk_mul_f32 v[20:21], v[232:233], v[20:21] op_sel:[1,0] op_sel_hi:[0,1]
	v_pk_mul_f32 v[32:33], v[236:237], v[16:17]
	v_pk_mul_f32 v[16:17], v[236:237], v[16:17] op_sel:[1,0] op_sel_hi:[0,1]
	v_add_f32_e32 v19, v18, v19
	v_sub_f32_e32 v24, v24, v25
	v_add_f32_e32 v20, v20, v21
	v_sub_f32_e32 v21, v26, v27
	v_add_f32_e32 v22, v22, v23
	v_sub_f32_e32 v23, v32, v33
	v_add_f32_e32 v25, v16, v17
	v_sub_f32_e32 v26, v34, v35
	v_cvt_pk_bf16_f32 v16, v24, v20
	v_cvt_pk_bf16_f32 v17, v21, v22
	v_cvt_pk_bf16_f32 v18, v23, v25
	v_cvt_pk_bf16_f32 v19, v26, v19
	global_store_dwordx4 v[30:31], v[16:19], off offset:256
	ds_read_b32 v24, v180
	v_ashrrev_i32_e32 v41, 31, v40
	s_waitcnt lgkmcnt(0)
	v_add_f32_e32 v24, v191, v24
	v_fmamk_f32 v24, v24, 0x3c800000, v188
	v_rsq_f32_e32 v24, v24
	s_nop 0
	v_pk_mul_f32 v[12:13], v[12:13], v[24:25] op_sel_hi:[1,0]
	v_pk_mul_f32 v[10:11], v[10:11], v[24:25] op_sel_hi:[1,0]
	v_pk_mul_f32 v[14:15], v[14:15], v[24:25] op_sel_hi:[1,0]
	v_pk_mul_f32 v[8:9], v[8:9], v[24:25] op_sel_hi:[1,0]
	v_pk_mul_f32 v[12:13], v[122:123], v[12:13]
	v_pk_mul_f32 v[10:11], v[124:125], v[10:11]
	v_pk_mul_f32 v[14:15], v[120:121], v[14:15]
	v_pk_mul_f32 v[8:9], v[126:127], v[8:9]
	s_waitcnt vmcnt(2)
	v_pk_mul_f32 v[24:25], v[240:241], v[12:13]
	v_pk_mul_f32 v[12:13], v[240:241], v[12:13] op_sel:[1,0] op_sel_hi:[0,1]
	s_waitcnt vmcnt(1)
	v_pk_mul_f32 v[30:31], v[246:247], v[10:11]
	v_pk_mul_f32 v[10:11], v[246:247], v[10:11] op_sel:[1,0] op_sel_hi:[0,1]
	v_pk_mul_f32 v[26:27], v[242:243], v[14:15]
	v_pk_mul_f32 v[14:15], v[242:243], v[14:15] op_sel:[1,0] op_sel_hi:[0,1]
	v_pk_mul_f32 v[28:29], v[244:245], v[8:9]
	v_pk_mul_f32 v[8:9], v[244:245], v[8:9] op_sel:[1,0] op_sel_hi:[0,1]
	v_add_f32_e32 v12, v12, v13
	v_add_f32_e32 v11, v10, v11
	v_sub_f32_e32 v24, v24, v25
	v_sub_f32_e32 v13, v26, v27
	v_add_f32_e32 v14, v14, v15
	v_sub_f32_e32 v15, v28, v29
	v_add_f32_e32 v25, v8, v9
	v_sub_f32_e32 v26, v30, v31
	v_cvt_pk_bf16_f32 v8, v24, v12
	v_cvt_pk_bf16_f32 v9, v13, v14
	v_cvt_pk_bf16_f32 v10, v15, v25
	v_cvt_pk_bf16_f32 v11, v26, v11
	ds_read_b32 v12, v181
	v_lshlrev_b64 v[14:15], s10, v[40:41]
	v_lshl_add_u64 v[160:161], v[14:15], 1, v[128:129]
	global_store_dwordx4 v[160:161], v[8:11], off
	s_waitcnt lgkmcnt(0)
	v_add_f32_e32 v12, v190, v12
	v_fmamk_f32 v12, v12, 0x3c800000, v188
	v_rsq_f32_e32 v12, v12
	s_nop 0
	v_pk_mul_f32 v[6:7], v[6:7], v[12:13] op_sel_hi:[1,0]
	v_pk_mul_f32 v[4:5], v[4:5], v[12:13] op_sel_hi:[1,0]
	v_pk_mul_f32 v[2:3], v[2:3], v[12:13] op_sel_hi:[1,0]
	v_pk_mul_f32 v[0:1], v[0:1], v[12:13] op_sel_hi:[1,0]
	v_pk_mul_f32 v[6:7], v[120:121], v[6:7]
	v_pk_mul_f32 v[4:5], v[122:123], v[4:5]
	v_pk_mul_f32 v[2:3], v[124:125], v[2:3]
	v_pk_mul_f32 v[0:1], v[126:127], v[0:1]
	v_pk_mul_f32 v[8:9], v[240:241], v[4:5]
	v_pk_mul_f32 v[4:5], v[240:241], v[4:5] op_sel:[1,0] op_sel_hi:[0,1]
	v_pk_mul_f32 v[10:11], v[242:243], v[6:7]
	v_pk_mul_f32 v[6:7], v[242:243], v[6:7] op_sel:[1,0] op_sel_hi:[0,1]
	v_pk_mul_f32 v[12:13], v[244:245], v[0:1]
	v_pk_mul_f32 v[0:1], v[244:245], v[0:1] op_sel:[1,0] op_sel_hi:[0,1]
	v_pk_mul_f32 v[14:15], v[246:247], v[2:3]
	v_pk_mul_f32 v[2:3], v[246:247], v[2:3] op_sel:[1,0] op_sel_hi:[0,1]
	v_sub_f32_e32 v8, v8, v9
	v_add_f32_e32 v4, v4, v5
	v_sub_f32_e32 v5, v10, v11
	v_add_f32_e32 v6, v6, v7
	v_sub_f32_e32 v7, v12, v13
	v_add_f32_e32 v0, v0, v1
	v_sub_f32_e32 v1, v14, v15
	v_add_f32_e32 v2, v2, v3
	v_cvt_pk_bf16_f32 v128, v8, v4
	v_cvt_pk_bf16_f32 v129, v5, v6
	v_cvt_pk_bf16_f32 v130, v7, v0
	v_cvt_pk_bf16_f32 v131, v1, v2
	s_andn2_b64 vcc, exec, s[8:9]
	s_mov_b64 s[8:9], -1
	global_store_dwordx4 v[160:161], v[128:131], off offset:256
	s_cbranch_vccnz .LBB0_506
